# G1: the next unit's operand loads stay in flight through the current unit (counted vmcnt at the join, full wait moved to the end-of-unit copies)
# speedup vs baseline: 1.0108x; 1.0041x over previous
; #define LBAR() do { asm volatile("s_waitcnt lgkmcnt(0)" ::: "memory"); __builtin_amdgcn_s_barrier(); asm volatile("" ::: "memory"); } while (0)
; DEV f32x4 mfma16(bf16x8 a, bf16x8 b, f32x4 c) { return __builtin_amdgcn_mfma_f32_16x16x32_bf16(a, b, c, 0, 0, 0); }
; DEV u32x4 pack8v(const f32x4 a, const f32x4 b) { u32x4 w; w.x = cvt_pk_bf16(a[0], a[1]); w.y = cvt_pk_bf16(a[2], a[3]); w.z = cvt_pk_bf16(b[0], b[1]); w.w = cvt_pk_bf16(b[2], b[3]); return w; }
; DEV void g1_phase(const Args& a, unsigned char* lds, int G) {
;     ...
;         const u32x4 qraw = qn, kraw = kn, vraw0 = vn0, vraw1 = vn1;
;         u32x4 gf[4];
; #pragma unroll
;         for (int pt = 0; pt < 4; ++pt) gf[pt] = gfn[pt];
;     ...
;         {
;             const int dir = w >> 2;
; #pragma unroll
;             for (int e = 0; e < 2; ++e) {
;                 const int dvt = (w & 3) * 2 + e;
;                 bf16x8 vf[2];
; #pragma unroll
;                 for (int ks = 0; ks < 2; ++ks) vf[ks] = *(const bf16x8*)(sVT + (dvt * 16 + ln) * QP + ks * 32 + kg * 8);
; #pragma unroll
;                 for (int p = 0; p < 2; ++p) {
;                     f32x4 acc[2];
; #pragma unroll
;                     for (int n = 0; n < 2; ++n) { acc[n] = (f32x4){0.f, 0.f, 0.f, 0.f};
; #pragma unroll
;                         for (int ks = 0; ks < 2; ++ks) { const bf16x8 kf = *(const bf16x8*)(sKhT + (dir * 64 + p * 32 + prow(n, ln)) * QP + ks * 32 + kg * 8); acc[n] = mfma16(kf, vf[ks], acc[n]); } }
;                     *(u32x4*)(KV + (((size_t)u * 2 + dir) * 128 + dvt * 16 + ln) * 64 + p * 32 + kg * 8) = pack8v(acc[0], acc[1]);
;                 }
;             }
;         }
;         LBAR();
.LBB0_1503:
	s_waitcnt vmcnt(0)
	ds_read_b128 v[14:17], v138
	ds_read_b128 v[18:21], v138 offset:64
	ds_read_b128 v[22:25], v139
	ds_read_b128 v[62:65], v139 offset:64
	ds_read_b128 v[66:69], v139 offset:576
	ds_read_b128 v[74:77], v139 offset:640
	v_lshl_add_u64 v[4:5], v[96:97], 0, v[86:87]
	v_add_co_u32_e32 v4, vcc, s53, v4
	ds_read_b128 v[106:109], v139 offset:5184
	ds_read_b128 v[110:113], v139 offset:5248
	s_waitcnt lgkmcnt(5)
	v_mfma_f32_16x16x32_bf16 v[26:29], v[22:25], v[14:17], 0
	v_addc_co_u32_e32 v5, vcc, 0, v5, vcc
	v_lshl_add_u64 v[92:93], v[92:93], 0, s[76:77]
	s_waitcnt lgkmcnt(3)
	v_mfma_f32_16x16x32_bf16 v[70:73], v[66:69], v[14:17], 0
	v_lshl_add_u64 v[96:97], v[96:97], 0, s[78:79]
	s_add_i32 s51, s51, s3
	s_mov_b32 s58, s54
	v_mfma_f32_16x16x32_bf16 v[26:29], v[62:65], v[18:21], v[26:29]
	ds_read_b128 v[102:105], v139 offset:4672
	s_waitcnt lgkmcnt(3)
	v_mfma_f32_16x16x32_bf16 v[70:73], v[74:77], v[18:21], v[70:73]
	s_nop 4
	v_cvt_pk_bf16_f32 v26, v26, v27
	v_cvt_pk_bf16_f32 v27, v28, v29
	s_nop 0
	v_cvt_pk_bf16_f32 v28, v70, v71
	v_cvt_pk_bf16_f32 v29, v72, v73
	global_store_dwordx4 v[4:5], v[26:29], off
	ds_read_b128 v[26:29], v139 offset:4608
	s_waitcnt lgkmcnt(0)
	v_mfma_f32_16x16x32_bf16 v[70:73], v[26:29], v[14:17], 0
	v_mfma_f32_16x16x32_bf16 v[14:17], v[106:109], v[14:17], 0
	v_mfma_f32_16x16x32_bf16 v[70:73], v[102:105], v[18:21], v[70:73]
	v_mfma_f32_16x16x32_bf16 v[14:17], v[110:113], v[18:21], v[14:17]
	s_nop 6
	v_cvt_pk_bf16_f32 v18, v70, v71
	v_cvt_pk_bf16_f32 v19, v72, v73
	v_cvt_pk_bf16_f32 v20, v14, v15
	v_cvt_pk_bf16_f32 v21, v16, v17
	global_store_dwordx4 v[4:5], v[18:21], off offset:64
	ds_read_b128 v[14:17], v140
	ds_read_b128 v[18:21], v140 offset:64
	s_waitcnt lgkmcnt(1)
	v_mfma_f32_16x16x32_bf16 v[22:25], v[22:25], v[14:17], 0
	v_lshl_add_u64 v[4:5], v[94:95], 0, v[86:87]
	v_add_co_u32_e32 v4, vcc, s53, v4
	s_waitcnt lgkmcnt(0)
	v_mfma_f32_16x16x32_bf16 v[22:25], v[62:65], v[18:21], v[22:25]
	v_addc_co_u32_e32 v5, vcc, 0, v5, vcc
	v_mov_b64_e32 v[72:73], v[32:33]
	v_mfma_f32_16x16x32_bf16 v[62:65], v[66:69], v[14:17], 0
	v_mov_b64_e32 v[68:69], v[40:41]
	s_nop 3
	v_cvt_pk_bf16_f32 v22, v22, v23
	v_cvt_pk_bf16_f32 v23, v24, v25
	v_mfma_f32_16x16x32_bf16 v[62:65], v[74:77], v[18:21], v[62:65]
	v_mov_b64_e32 v[76:77], v[36:37]
	v_lshl_add_u64 v[94:95], v[94:95], 0, s[78:79]
	s_andn2_b64 vcc, exec, s[82:83]
	v_mov_b64_e32 v[74:75], v[34:35]
	v_mov_b64_e32 v[70:71], v[30:31]
	s_nop 2
	v_cvt_pk_bf16_f32 v24, v62, v63
	v_cvt_pk_bf16_f32 v25, v64, v65
	global_store_dwordx4 v[4:5], v[22:25], off offset:2048
	v_mov_b64_e32 v[64:65], v[44:45]
	v_mov_b64_e32 v[66:67], v[38:39]
	v_mfma_f32_16x16x32_bf16 v[22:25], v[26:29], v[14:17], 0
	v_mov_b64_e32 v[26:27], v[46:47]
	v_mov_b64_e32 v[62:63], v[42:43]
	v_mov_b64_e32 v[28:29], v[48:49]
	v_mfma_f32_16x16x32_bf16 v[14:17], v[106:109], v[14:17], 0
	v_mfma_f32_16x16x32_bf16 v[22:25], v[102:105], v[18:21], v[22:25]
	v_mfma_f32_16x16x32_bf16 v[14:17], v[110:113], v[18:21], v[14:17]
	s_nop 6
	v_cvt_pk_bf16_f32 v18, v22, v23
	v_cvt_pk_bf16_f32 v19, v24, v25
	v_cvt_pk_bf16_f32 v20, v14, v15
	v_cvt_pk_bf16_f32 v21, v16, v17
	global_store_dwordx4 v[4:5], v[18:21], off offset:2112
	s_waitcnt lgkmcnt(0)
	v_mov_b64_e32 v[22:23], v[50:51]
	v_mov_b64_e32 v[18:19], v[54:55]
	v_mov_b64_e32 v[14:15], v[58:59]
	v_mov_b64_e32 v[24:25], v[52:53]
	v_mov_b64_e32 v[20:21], v[56:57]
	v_mov_b64_e32 v[16:17], v[60:61]
	s_cbranch_vccz .LBB0_1548

; #define G1_WLOAD(h_) do { const float* wg_ = a.in[gdir ? I_WGB : I_WGF] + (h_) * 64 + dkt * 16 + ln; float wv_[8]; \
;         _Pragma("unroll") for (int j = 0; j < 8; ++j) wv_[j] = (kg < 2) ? wg_[(kg * 8 + j) * 256] : 0.f; \
;         const u32x4 wp_ = pack8(wv_); wfrag = __builtin_bit_cast(bf16x8, wp_); bias4 = *(const f32x4*)(a.in[gdir ? I_BGB : I_BGF] + (h_) * 64 + dkt * 16 + kg * 4); } while (0)
; DEV void g1_phase(const Args& a, unsigned char* lds, int G) {
;     ...
;     u32x4 qn, kn, vn0, vn1, gfn[4];
;     if ((int)blockIdx.x < NU_ALL) G1_LOAD((int)blockIdx.x);
;     bf16x8 wfrag; f32x4 bias4; int hcur = blockIdx.x & 3;
;     G1_WLOAD(hcur);
;     for (int u = blockIdx.x; u < NU_ALL; u += G) {
;         int b, c, h, row0; gla_unit_rows(u, b, c, h, row0); const bool lat = u < NU_LAT;
;         if (h != hcur) { hcur = h; G1_WLOAD(h); }
.LBB0_1521:
	s_or_b64 exec, exec, s[0:1]
	s_lshl_b32 s0, s55, 6
	s_lshl_b32 s70, s0, 2
	v_lshl_add_u64 v[4:5], v[90:91], 0, s[70:71]
	global_load_dwordx4 v[6:9], v[4:5], off
	s_waitcnt vmcnt(1)
	v_cvt_pk_bf16_f32 v10, v10, v3
	v_cvt_pk_bf16_f32 v11, v12, v11
	v_cvt_pk_bf16_f32 v12, v30, v13
	v_cvt_pk_bf16_f32 v13, v32, v31
	s_mov_b32 s81, s55
	s_waitcnt vmcnt(0)

; DEV f32x4 mfma16(bf16x8 a, bf16x8 b, f32x4 c) { return __builtin_amdgcn_mfma_f32_16x16x32_bf16(a, b, c, 0, 0, 0); }
; #define DPP_SHR(x_, n_) __builtin_bit_cast(float, __builtin_amdgcn_update_dpp(0, __builtin_bit_cast(int, (x_)), 0x110 | (n_), 0xf, 0xf, true))
; DEV void g1_phase(const Args& a, unsigned char* lds, int G) {
;     ...
;         if (u + G < NU_ALL) G1_LOAD(u + G);
;         {
;             float gl[4][4], cs[4][4], tot[4];
; #pragma unroll
;             for (int pt = 0; pt < 4; ++pt) {
;                 f32x4 pre = mfma16(wfrag, __builtin_bit_cast(bf16x8, gf[pt]), bias4);
; #pragma unroll
;                 for (int r = 0; r < 4; ++r) { const float x = pre[r]; const float ls = (fminf(x, 0.f) - __logf(1.f + __expf(-fabsf(x)))) * (1.f / 16.f); gl[pt][r] = ls;
;                     float sc = ls; sc += DPP_SHR(sc, 1); sc += DPP_SHR(sc, 2); sc += DPP_SHR(sc, 4); sc += DPP_SHR(sc, 8); cs[pt][r] = sc; }
.LBB0_1532:
	s_waitcnt vmcnt(8)
	v_mfma_f32_16x16x32_bf16 v[74:77], v[10:13], v[74:77], v[6:9]
	v_mfma_f32_16x16x32_bf16 v[70:73], v[10:13], v[70:73], v[6:9]
	v_mfma_f32_16x16x32_bf16 v[62:65], v[10:13], v[62:65], v[6:9]
	s_nop 5
	v_max_f32_e32 v3, v74, v74
	v_min_f32_e32 v4, 0, v3
	v_mul_f32_e64 v3, |v74|, s49
	v_exp_f32_e32 v3, v3
	s_nop 0
	v_add_f32_e32 v3, 1.0, v3
	v_cmp_gt_f32_e32 vcc, s33, v3
	s_nop 1
	v_cndmask_b32_e64 v5, 0, 32, vcc
	v_ldexp_f32 v3, v3, v5
	v_log_f32_e32 v3, v3
	s_nop 0
	v_mul_f32_e32 v5, 0x3f317217, v3
	v_fma_f32 v5, v3, s92, -v5
	v_fmac_f32_e32 v5, 0x3377d1cf, v3
	v_fmac_f32_e32 v5, 0x3f317217, v3
	v_cmp_lt_f32_e64 s[0:1], |v3|, s52
	s_nop 1
	v_cndmask_b32_e64 v3, v3, v5, s[0:1]
	v_cndmask_b32_e32 v5, 0, v141, vcc
	v_sub_f32_e32 v74, v3, v5
	v_max_f32_e32 v3, v75, v75
	v_min_f32_e32 v5, 0, v3
	v_mul_f32_e64 v3, |v75|, s49
	v_exp_f32_e32 v3, v3
	s_nop 0
	v_add_f32_e32 v3, 1.0, v3
	v_cmp_gt_f32_e32 vcc, s33, v3
	s_nop 1
	v_cndmask_b32_e64 v75, 0, 32, vcc
	v_ldexp_f32 v3, v3, v75
	v_log_f32_e32 v3, v3
	s_nop 0
	v_mul_f32_e32 v75, 0x3f317217, v3
	v_fma_f32 v75, v3, s92, -v75
	v_fmac_f32_e32 v75, 0x3377d1cf, v3
	v_fmac_f32_e32 v75, 0x3f317217, v3
	v_cmp_lt_f32_e64 s[0:1], |v3|, s52
	s_nop 1
	v_cndmask_b32_e64 v3, v3, v75, s[0:1]
	v_cndmask_b32_e32 v75, 0, v141, vcc
	v_sub_f32_e32 v75, v3, v75
	v_pk_add_f32 v[74:75], v[4:5], v[74:75] neg_lo:[0,1] neg_hi:[0,1]
	v_max_f32_e32 v3, v76, v76
	v_pk_mul_f32 v[4:5], v[74:75], s[80:81] op_sel_hi:[1,0]
	s_nop 1
	v_mov_b32_dpp v102, v4 row_shr:1 row_mask:0xf bank_mask:0xf bound_ctrl:1
	v_mov_b32_dpp v103, v5 row_shr:1 row_mask:0xf bank_mask:0xf bound_ctrl:1
	v_pk_fma_f32 v[74:75], v[74:75], s[80:81], v[102:103] op_sel_hi:[1,0,1]
	s_nop 1
	v_mov_b32_dpp v102, v74 row_shr:2 row_mask:0xf bank_mask:0xf bound_ctrl:1
	v_mov_b32_dpp v103, v75 row_shr:2 row_mask:0xf bank_mask:0xf bound_ctrl:1
	v_pk_add_f32 v[74:75], v[74:75], v[102:103]
	s_nop 1
	v_mov_b32_dpp v102, v74 row_shr:4 row_mask:0xf bank_mask:0xf bound_ctrl:1
	v_mov_b32_dpp v103, v75 row_shr:4 row_mask:0xf bank_mask:0xf bound_ctrl:1
	v_pk_add_f32 v[74:75], v[74:75], v[102:103]
	s_nop 1
	v_mov_b32_dpp v102, v74 row_shr:8 row_mask:0xf bank_mask:0xf bound_ctrl:1
	v_mov_b32_dpp v103, v75 row_shr:8 row_mask:0xf bank_mask:0xf bound_ctrl:1
	v_pk_add_f32 v[74:75], v[74:75], v[102:103]
	v_min_f32_e32 v102, 0, v3
	v_mul_f32_e64 v3, |v76|, s49
	v_exp_f32_e32 v3, v3
	s_nop 0
	v_add_f32_e32 v3, 1.0, v3
	v_cmp_gt_f32_e32 vcc, s33, v3
	s_nop 1
	v_cndmask_b32_e64 v76, 0, 32, vcc
	v_ldexp_f32 v3, v3, v76
	v_log_f32_e32 v3, v3
	s_nop 0
	v_mul_f32_e32 v76, 0x3f317217, v3
	v_fma_f32 v76, v3, s92, -v76
	v_fmac_f32_e32 v76, 0x3377d1cf, v3
	v_fmac_f32_e32 v76, 0x3f317217, v3
	v_cmp_lt_f32_e64 s[0:1], |v3|, s52
	s_nop 1
	v_cndmask_b32_e64 v3, v3, v76, s[0:1]
	v_cndmask_b32_e32 v76, 0, v141, vcc
	v_sub_f32_e32 v76, v3, v76
	v_max_f32_e32 v3, v77, v77
	v_min_f32_e32 v103, 0, v3
	v_mul_f32_e64 v3, |v77|, s49
	v_exp_f32_e32 v3, v3
	s_nop 0
	v_add_f32_e32 v3, 1.0, v3
	v_cmp_gt_f32_e32 vcc, s33, v3
	s_nop 1
	v_cndmask_b32_e64 v77, 0, 32, vcc
	v_ldexp_f32 v3, v3, v77
	v_log_f32_e32 v3, v3
	s_nop 0
	v_mul_f32_e32 v77, 0x3f317217, v3
	v_fma_f32 v77, v3, s92, -v77
	v_fmac_f32_e32 v77, 0x3377d1cf, v3
	v_fmac_f32_e32 v77, 0x3f317217, v3
	v_cmp_lt_f32_e64 s[0:1], |v3|, s52
	s_nop 1
	v_cndmask_b32_e64 v3, v3, v77, s[0:1]
	v_cndmask_b32_e32 v77, 0, v141, vcc
	v_sub_f32_e32 v77, v3, v77
	v_pk_add_f32 v[76:77], v[102:103], v[76:77] neg_lo:[0,1] neg_hi:[0,1]
	v_max_f32_e32 v3, v70, v70
	v_pk_mul_f32 v[102:103], v[76:77], s[80:81] op_sel_hi:[1,0]
	s_nop 1
	v_mov_b32_dpp v104, v102 row_shr:1 row_mask:0xf bank_mask:0xf bound_ctrl:1
	v_mov_b32_dpp v105, v103 row_shr:1 row_mask:0xf bank_mask:0xf bound_ctrl:1
	v_pk_fma_f32 v[76:77], v[76:77], s[80:81], v[104:105] op_sel_hi:[1,0,1]
	s_nop 1
	v_mov_b32_dpp v104, v76 row_shr:2 row_mask:0xf bank_mask:0xf bound_ctrl:1
	v_mov_b32_dpp v105, v77 row_shr:2 row_mask:0xf bank_mask:0xf bound_ctrl:1
	v_pk_add_f32 v[76:77], v[76:77], v[104:105]
	s_nop 1
	v_mov_b32_dpp v104, v76 row_shr:4 row_mask:0xf bank_mask:0xf bound_ctrl:1
	v_mov_b32_dpp v105, v77 row_shr:4 row_mask:0xf bank_mask:0xf bound_ctrl:1
	v_pk_add_f32 v[76:77], v[76:77], v[104:105]
	s_nop 1
	v_mov_b32_dpp v104, v76 row_shr:8 row_mask:0xf bank_mask:0xf bound_ctrl:1
	v_mov_b32_dpp v105, v77 row_shr:8 row_mask:0xf bank_mask:0xf bound_ctrl:1
	v_pk_add_f32 v[76:77], v[76:77], v[104:105]
	v_min_f32_e32 v104, 0, v3
	v_mul_f32_e64 v3, |v70|, s49
	v_exp_f32_e32 v3, v3
	s_nop 0
	v_add_f32_e32 v3, 1.0, v3
	v_cmp_gt_f32_e32 vcc, s33, v3
	s_nop 1
	v_cndmask_b32_e64 v70, 0, 32, vcc
	v_ldexp_f32 v3, v3, v70
	v_log_f32_e32 v3, v3
	s_nop 0
	v_mul_f32_e32 v70, 0x3f317217, v3
	v_fma_f32 v70, v3, s92, -v70
	v_fmac_f32_e32 v70, 0x3377d1cf, v3
	v_fmac_f32_e32 v70, 0x3f317217, v3
	v_cmp_lt_f32_e64 s[0:1], |v3|, s52
	s_nop 1
	v_cndmask_b32_e64 v3, v3, v70, s[0:1]
	v_cndmask_b32_e32 v70, 0, v141, vcc
	v_sub_f32_e32 v70, v3, v70
	v_max_f32_e32 v3, v71, v71
	v_min_f32_e32 v105, 0, v3
	v_mul_f32_e64 v3, |v71|, s49
	v_exp_f32_e32 v3, v3
	s_nop 0
	v_add_f32_e32 v3, 1.0, v3
	v_cmp_gt_f32_e32 vcc, s33, v3
	s_nop 1
	v_cndmask_b32_e64 v71, 0, 32, vcc
	v_ldexp_f32 v3, v3, v71
	v_log_f32_e32 v3, v3
	s_nop 0
	v_mul_f32_e32 v71, 0x3f317217, v3
	v_fma_f32 v71, v3, s92, -v71
	v_fmac_f32_e32 v71, 0x3377d1cf, v3
	v_fmac_f32_e32 v71, 0x3f317217, v3
	v_cmp_lt_f32_e64 s[0:1], |v3|, s52
	s_nop 1
	v_cndmask_b32_e64 v3, v3, v71, s[0:1]
	v_cndmask_b32_e32 v71, 0, v141, vcc
	v_sub_f32_e32 v71, v3, v71
	v_pk_add_f32 v[70:71], v[104:105], v[70:71] neg_lo:[0,1] neg_hi:[0,1]
	v_max_f32_e32 v3, v72, v72
; DEV f32x4 mfma16(bf16x8 a, bf16x8 b, f32x4 c) { return __builtin_amdgcn_mfma_f32_16x16x32_bf16(a, b, c, 0, 0, 0); }
; #define DPP_SHR(x_, n_) __builtin_bit_cast(float, __builtin_amdgcn_update_dpp(0, __builtin_bit_cast(int, (x_)), 0x110 | (n_), 0xf, 0xf, true))
; DEV void g1_phase(const Args& a, unsigned char* lds, int G) {
;     ...
;             for (int pt = 0; pt < 4; ++pt) {
;                 f32x4 pre = mfma16(wfrag, __builtin_bit_cast(bf16x8, gf[pt]), bias4);
; #pragma unroll
;                 for (int r = 0; r < 4; ++r) { const float x = pre[r]; const float ls = (fminf(x, 0.f) - __logf(1.f + __expf(-fabsf(x)))) * (1.f / 16.f); gl[pt][r] = ls;
;                     float sc = ls; sc += DPP_SHR(sc, 1); sc += DPP_SHR(sc, 2); sc += DPP_SHR(sc, 4); sc += DPP_SHR(sc, 8); cs[pt][r] = sc; }
;             }
; #pragma unroll
;             for (int r = 0; r < 4; ++r) { float off = 0.f;
; #pragma unroll
;                 for (int pt = 0; pt < 4; ++pt) { const float tt = __shfl(cs[pt][r], (lane & 48) | 15); cs[pt][r] += off; off += tt; }
	v_pk_mul_f32 v[104:105], v[70:71], s[80:81] op_sel_hi:[1,0]
	s_nop 1
	v_mov_b32_dpp v106, v104 row_shr:1 row_mask:0xf bank_mask:0xf bound_ctrl:1
	v_mov_b32_dpp v107, v105 row_shr:1 row_mask:0xf bank_mask:0xf bound_ctrl:1
	v_pk_fma_f32 v[70:71], v[70:71], s[80:81], v[106:107] op_sel_hi:[1,0,1]
	s_nop 1
	v_mov_b32_dpp v106, v70 row_shr:2 row_mask:0xf bank_mask:0xf bound_ctrl:1
	v_mov_b32_dpp v107, v71 row_shr:2 row_mask:0xf bank_mask:0xf bound_ctrl:1
	v_pk_add_f32 v[70:71], v[70:71], v[106:107]
	s_nop 1
	v_mov_b32_dpp v106, v70 row_shr:4 row_mask:0xf bank_mask:0xf bound_ctrl:1
	v_mov_b32_dpp v107, v71 row_shr:4 row_mask:0xf bank_mask:0xf bound_ctrl:1
	v_pk_add_f32 v[70:71], v[70:71], v[106:107]
	s_nop 1
	v_mov_b32_dpp v106, v70 row_shr:8 row_mask:0xf bank_mask:0xf bound_ctrl:1
	v_mov_b32_dpp v107, v71 row_shr:8 row_mask:0xf bank_mask:0xf bound_ctrl:1
	v_pk_add_f32 v[70:71], v[70:71], v[106:107]
	v_min_f32_e32 v106, 0, v3
	v_mul_f32_e64 v3, |v72|, s49
	v_exp_f32_e32 v3, v3
	ds_bpermute_b32 v142, v81, v70
	ds_bpermute_b32 v143, v81, v71
	v_add_f32_e32 v3, 1.0, v3
	v_cmp_gt_f32_e32 vcc, s33, v3
	s_nop 1
	v_cndmask_b32_e64 v72, 0, 32, vcc
	v_ldexp_f32 v3, v3, v72
	v_log_f32_e32 v3, v3
	s_nop 0
	v_mul_f32_e32 v72, 0x3f317217, v3
	v_fma_f32 v72, v3, s92, -v72
	v_fmac_f32_e32 v72, 0x3377d1cf, v3
	v_fmac_f32_e32 v72, 0x3f317217, v3
	v_cmp_lt_f32_e64 s[0:1], |v3|, s52
	s_nop 1
	v_cndmask_b32_e64 v3, v3, v72, s[0:1]
	v_cndmask_b32_e32 v72, 0, v141, vcc
	v_sub_f32_e32 v72, v3, v72
	v_max_f32_e32 v3, v73, v73
	v_min_f32_e32 v107, 0, v3
	v_mul_f32_e64 v3, |v73|, s49
	v_exp_f32_e32 v3, v3
	s_nop 0
	v_add_f32_e32 v3, 1.0, v3
	v_cmp_gt_f32_e32 vcc, s33, v3
	s_nop 1
	v_cndmask_b32_e64 v73, 0, 32, vcc
	v_ldexp_f32 v3, v3, v73
	v_log_f32_e32 v3, v3
	s_nop 0
	v_mul_f32_e32 v73, 0x3f317217, v3
	v_fma_f32 v73, v3, s92, -v73
	v_fmac_f32_e32 v73, 0x3377d1cf, v3
	v_fmac_f32_e32 v73, 0x3f317217, v3
	v_cmp_lt_f32_e64 s[0:1], |v3|, s52
	s_nop 1
	v_cndmask_b32_e64 v3, v3, v73, s[0:1]
	v_cndmask_b32_e32 v73, 0, v141, vcc
	v_sub_f32_e32 v73, v3, v73
	v_pk_add_f32 v[72:73], v[106:107], v[72:73] neg_lo:[0,1] neg_hi:[0,1]
	s_nop 0
	v_pk_mul_f32 v[106:107], v[72:73], s[80:81] op_sel_hi:[1,0]
	s_nop 1
	v_mov_b32_dpp v108, v106 row_shr:1 row_mask:0xf bank_mask:0xf bound_ctrl:1
	v_mov_b32_dpp v109, v107 row_shr:1 row_mask:0xf bank_mask:0xf bound_ctrl:1
	v_pk_fma_f32 v[72:73], v[72:73], s[80:81], v[108:109] op_sel_hi:[1,0,1]
	s_nop 1
	v_mov_b32_dpp v108, v72 row_shr:2 row_mask:0xf bank_mask:0xf bound_ctrl:1
	v_mov_b32_dpp v109, v73 row_shr:2 row_mask:0xf bank_mask:0xf bound_ctrl:1
	v_pk_add_f32 v[72:73], v[72:73], v[108:109]
	s_nop 1
	v_mov_b32_dpp v108, v72 row_shr:4 row_mask:0xf bank_mask:0xf bound_ctrl:1
	v_mov_b32_dpp v109, v73 row_shr:4 row_mask:0xf bank_mask:0xf bound_ctrl:1
	v_pk_add_f32 v[72:73], v[72:73], v[108:109]
	s_nop 1
	v_mov_b32_dpp v108, v72 row_shr:8 row_mask:0xf bank_mask:0xf bound_ctrl:1
	v_mov_b32_dpp v109, v73 row_shr:8 row_mask:0xf bank_mask:0xf bound_ctrl:1
	v_pk_add_f32 v[72:73], v[72:73], v[108:109]
	v_mfma_f32_16x16x32_bf16 v[108:111], v[10:13], v[66:69], v[6:9]
	s_nop 7
	v_max_f32_e32 v3, v108, v108
	v_min_f32_e32 v66, 0, v3
	v_mul_f32_e64 v3, |v108|, s49
	v_exp_f32_e32 v3, v3
	s_nop 0
	v_add_f32_e32 v3, 1.0, v3
	v_cmp_gt_f32_e32 vcc, s33, v3
	s_nop 1
	v_cndmask_b32_e64 v67, 0, 32, vcc
	v_ldexp_f32 v3, v3, v67
	v_log_f32_e32 v3, v3
	s_nop 0
	v_mul_f32_e32 v67, 0x3f317217, v3
	v_fma_f32 v67, v3, s92, -v67
	v_fmac_f32_e32 v67, 0x3377d1cf, v3
	v_fmac_f32_e32 v67, 0x3f317217, v3
	v_cmp_lt_f32_e64 s[0:1], |v3|, s52
	s_nop 1
	v_cndmask_b32_e64 v3, v3, v67, s[0:1]
	v_cndmask_b32_e32 v67, 0, v141, vcc
	v_sub_f32_e32 v68, v3, v67
	v_max_f32_e32 v3, v109, v109
	v_min_f32_e32 v67, 0, v3
	v_mul_f32_e64 v3, |v109|, s49
	v_exp_f32_e32 v3, v3
	s_nop 0
	v_add_f32_e32 v3, 1.0, v3
	v_cmp_gt_f32_e32 vcc, s33, v3
	s_nop 1
	v_cndmask_b32_e64 v69, 0, 32, vcc
	v_ldexp_f32 v3, v3, v69
	v_log_f32_e32 v3, v3
	s_nop 0
	v_mul_f32_e32 v69, 0x3f317217, v3
	v_fma_f32 v69, v3, s92, -v69
	v_fmac_f32_e32 v69, 0x3377d1cf, v3
	v_fmac_f32_e32 v69, 0x3f317217, v3
	v_cmp_lt_f32_e64 s[0:1], |v3|, s52
	s_nop 1
	v_cndmask_b32_e64 v3, v3, v69, s[0:1]
	v_cndmask_b32_e32 v69, 0, v141, vcc
	v_sub_f32_e32 v69, v3, v69
	v_pk_add_f32 v[66:67], v[66:67], v[68:69] neg_lo:[0,1] neg_hi:[0,1]
	v_max_f32_e32 v3, v110, v110
	v_pk_mul_f32 v[108:109], v[66:67], s[80:81] op_sel_hi:[1,0]
	s_nop 1
	v_mov_b32_dpp v68, v108 row_shr:1 row_mask:0xf bank_mask:0xf bound_ctrl:1
	v_mov_b32_dpp v69, v109 row_shr:1 row_mask:0xf bank_mask:0xf bound_ctrl:1
	v_pk_fma_f32 v[66:67], v[66:67], s[80:81], v[68:69] op_sel_hi:[1,0,1]
	s_nop 1
	v_mov_b32_dpp v68, v66 row_shr:2 row_mask:0xf bank_mask:0xf bound_ctrl:1
	v_mov_b32_dpp v69, v67 row_shr:2 row_mask:0xf bank_mask:0xf bound_ctrl:1
	v_pk_add_f32 v[66:67], v[66:67], v[68:69]
	s_nop 1
	v_mov_b32_dpp v68, v66 row_shr:4 row_mask:0xf bank_mask:0xf bound_ctrl:1
	v_mov_b32_dpp v69, v67 row_shr:4 row_mask:0xf bank_mask:0xf bound_ctrl:1
	v_pk_add_f32 v[66:67], v[66:67], v[68:69]
	s_nop 1
	v_mov_b32_dpp v68, v66 row_shr:8 row_mask:0xf bank_mask:0xf bound_ctrl:1
	v_mov_b32_dpp v69, v67 row_shr:8 row_mask:0xf bank_mask:0xf bound_ctrl:1
	v_pk_add_f32 v[66:67], v[66:67], v[68:69]
	v_min_f32_e32 v68, 0, v3
	v_mul_f32_e64 v3, |v110|, s49
	v_exp_f32_e32 v3, v3
	ds_bpermute_b32 v144, v81, v66
	ds_bpermute_b32 v145, v81, v67
	v_add_f32_e32 v3, 1.0, v3
	v_cmp_gt_f32_e32 vcc, s33, v3
	s_nop 1
	v_cndmask_b32_e64 v69, 0, 32, vcc
	v_ldexp_f32 v3, v3, v69
	v_log_f32_e32 v3, v3
	s_nop 0
	v_mul_f32_e32 v69, 0x3f317217, v3
	v_fma_f32 v69, v3, s92, -v69
	v_fmac_f32_e32 v69, 0x3377d1cf, v3
; DEV f32x4 mfma16(bf16x8 a, bf16x8 b, f32x4 c) { return __builtin_amdgcn_mfma_f32_16x16x32_bf16(a, b, c, 0, 0, 0); }
; #define DPP_SHR(x_, n_) __builtin_bit_cast(float, __builtin_amdgcn_update_dpp(0, __builtin_bit_cast(int, (x_)), 0x110 | (n_), 0xf, 0xf, true))
; DEV void g1_phase(const Args& a, unsigned char* lds, int G) {
;     ...
;             for (int pt = 0; pt < 4; ++pt) {
;                 f32x4 pre = mfma16(wfrag, __builtin_bit_cast(bf16x8, gf[pt]), bias4);
; #pragma unroll
;                 for (int r = 0; r < 4; ++r) { const float x = pre[r]; const float ls = (fminf(x, 0.f) - __logf(1.f + __expf(-fabsf(x)))) * (1.f / 16.f); gl[pt][r] = ls;
;                     float sc = ls; sc += DPP_SHR(sc, 1); sc += DPP_SHR(sc, 2); sc += DPP_SHR(sc, 4); sc += DPP_SHR(sc, 8); cs[pt][r] = sc; }
;             }
; #pragma unroll
;             for (int r = 0; r < 4; ++r) { float off = 0.f;
; #pragma unroll
;                 for (int pt = 0; pt < 4; ++pt) { const float tt = __shfl(cs[pt][r], (lane & 48) | 15); cs[pt][r] += off; off += tt; }
	v_fmac_f32_e32 v69, 0x3f317217, v3
	v_cmp_lt_f32_e64 s[0:1], |v3|, s52
	s_nop 1
	v_cndmask_b32_e64 v3, v3, v69, s[0:1]
	v_cndmask_b32_e32 v69, 0, v141, vcc
	v_sub_f32_e32 v110, v3, v69
	v_max_f32_e32 v3, v111, v111
	v_min_f32_e32 v69, 0, v3
	v_mul_f32_e64 v3, |v111|, s49
	v_exp_f32_e32 v3, v3
	s_nop 0
	v_add_f32_e32 v3, 1.0, v3
	v_cmp_gt_f32_e32 vcc, s33, v3
	s_nop 1
	v_cndmask_b32_e64 v99, 0, 32, vcc
	v_ldexp_f32 v3, v3, v99
	v_log_f32_e32 v3, v3
	s_nop 0
	v_mul_f32_e32 v99, 0x3f317217, v3
	v_fma_f32 v99, v3, s92, -v99
	v_fmac_f32_e32 v99, 0x3377d1cf, v3
	v_fmac_f32_e32 v99, 0x3f317217, v3
	v_cmp_lt_f32_e64 s[0:1], |v3|, s52
	s_nop 1
	v_cndmask_b32_e64 v3, v3, v99, s[0:1]
	v_cndmask_b32_e32 v99, 0, v141, vcc
	v_sub_f32_e32 v111, v3, v99
	v_max_f32_e32 v3, v62, v62
	v_min_f32_e32 v114, 0, v3
	v_mul_f32_e64 v3, |v62|, s49
	v_exp_f32_e32 v3, v3
	v_pk_add_f32 v[68:69], v[68:69], v[110:111] neg_lo:[0,1] neg_hi:[0,1]
	v_add_f32_e32 v3, 1.0, v3
	v_cmp_gt_f32_e32 vcc, s33, v3
	v_pk_mul_f32 v[110:111], v[68:69], s[80:81] op_sel_hi:[1,0]
	s_nop 0
	v_cndmask_b32_e64 v62, 0, 32, vcc
	v_ldexp_f32 v3, v3, v62
	v_log_f32_e32 v3, v3
	s_nop 0
	v_mul_f32_e32 v62, 0x3f317217, v3
	v_fma_f32 v62, v3, s92, -v62
	v_fmac_f32_e32 v62, 0x3377d1cf, v3
	v_fmac_f32_e32 v62, 0x3f317217, v3
	v_cmp_lt_f32_e64 s[0:1], |v3|, s52
	s_nop 1
	v_cndmask_b32_e64 v3, v3, v62, s[0:1]
	v_cndmask_b32_e32 v62, 0, v141, vcc
	v_sub_f32_e32 v116, v3, v62
	v_max_f32_e32 v3, v63, v63
	v_min_f32_e32 v115, 0, v3
	v_mul_f32_e64 v3, |v63|, s49
	v_exp_f32_e32 v3, v3
	s_nop 0
	v_add_f32_e32 v3, 1.0, v3
	v_cmp_gt_f32_e32 vcc, s33, v3
	s_nop 1
	v_cndmask_b32_e64 v62, 0, 32, vcc
	v_ldexp_f32 v3, v3, v62
	v_log_f32_e32 v3, v3
	s_nop 0
	v_mul_f32_e32 v62, 0x3f317217, v3
	v_fma_f32 v62, v3, s92, -v62
	v_fmac_f32_e32 v62, 0x3377d1cf, v3
	v_fmac_f32_e32 v62, 0x3f317217, v3
	v_cmp_lt_f32_e64 s[0:1], |v3|, s52
	s_nop 1
	v_cndmask_b32_e64 v3, v3, v62, s[0:1]
	v_cndmask_b32_e32 v62, 0, v141, vcc
	v_sub_f32_e32 v117, v3, v62
	v_max_f32_e32 v3, v64, v64
	v_min_f32_e32 v62, 0, v3
	v_mul_f32_e64 v3, |v64|, s49
	v_exp_f32_e32 v3, v3
	s_nop 0
	v_add_f32_e32 v3, 1.0, v3
	v_cmp_gt_f32_e32 vcc, s33, v3
	s_nop 1
	v_cndmask_b32_e64 v63, 0, 32, vcc
	v_ldexp_f32 v3, v3, v63
	v_log_f32_e32 v3, v3
	s_nop 0
	v_mul_f32_e32 v63, 0x3f317217, v3
	v_fma_f32 v63, v3, s92, -v63
	v_fmac_f32_e32 v63, 0x3377d1cf, v3
	v_fmac_f32_e32 v63, 0x3f317217, v3
	v_cmp_lt_f32_e64 s[0:1], |v3|, s52
	s_nop 1
	v_cndmask_b32_e64 v3, v3, v63, s[0:1]
	v_cndmask_b32_e32 v63, 0, v141, vcc
	v_sub_f32_e32 v64, v3, v63
	v_max_f32_e32 v3, v65, v65
	v_min_f32_e32 v63, 0, v3
	v_mul_f32_e64 v3, |v65|, s49
	v_exp_f32_e32 v3, v3
	s_nop 0
	v_add_f32_e32 v3, 1.0, v3
	v_cmp_gt_f32_e32 vcc, s33, v3
	s_nop 1
	v_cndmask_b32_e64 v65, 0, 32, vcc
	v_ldexp_f32 v3, v3, v65
	v_log_f32_e32 v3, v3
	s_nop 0
	v_mul_f32_e32 v65, 0x3f317217, v3
	v_fma_f32 v65, v3, s92, -v65
	v_fmac_f32_e32 v65, 0x3377d1cf, v3
	v_fmac_f32_e32 v65, 0x3f317217, v3
	v_cmp_lt_f32_e64 s[0:1], |v3|, s52
	s_nop 1
	v_cndmask_b32_e64 v3, v3, v65, s[0:1]
	v_cndmask_b32_e32 v65, 0, v141, vcc
	v_sub_f32_e32 v65, v3, v65
	v_pk_add_f32 v[62:63], v[62:63], v[64:65] neg_lo:[0,1] neg_hi:[0,1]
	s_nop 0
	v_pk_mul_f32 v[112:113], v[62:63], s[80:81] op_sel_hi:[1,0]
	s_nop 1
	v_mov_b32_dpp v64, v112 row_shr:1 row_mask:0xf bank_mask:0xf bound_ctrl:1
	v_mov_b32_dpp v65, v113 row_shr:1 row_mask:0xf bank_mask:0xf bound_ctrl:1
	v_pk_fma_f32 v[62:63], v[62:63], s[80:81], v[64:65] op_sel_hi:[1,0,1]
	s_nop 1
	v_mov_b32_dpp v64, v62 row_shr:2 row_mask:0xf bank_mask:0xf bound_ctrl:1
	v_mov_b32_dpp v65, v63 row_shr:2 row_mask:0xf bank_mask:0xf bound_ctrl:1
	v_pk_add_f32 v[62:63], v[62:63], v[64:65]
	s_nop 1
	v_mov_b32_dpp v64, v62 row_shr:4 row_mask:0xf bank_mask:0xf bound_ctrl:1
	v_mov_b32_dpp v65, v63 row_shr:4 row_mask:0xf bank_mask:0xf bound_ctrl:1
	v_pk_add_f32 v[62:63], v[62:63], v[64:65]
	s_nop 1
	v_mov_b32_dpp v64, v62 row_shr:8 row_mask:0xf bank_mask:0xf bound_ctrl:1
	v_mov_b32_dpp v65, v63 row_shr:8 row_mask:0xf bank_mask:0xf bound_ctrl:1
	v_pk_add_f32 v[118:119], v[62:63], v[64:65]
	ds_bpermute_b32 v64, v81, v74
	ds_bpermute_b32 v65, v81, v75
	v_pk_add_f32 v[62:63], v[74:75], 0 op_sel_hi:[1,0]
	v_pk_add_f32 v[74:75], v[114:115], v[116:117] neg_lo:[0,1] neg_hi:[0,1]
	s_waitcnt lgkmcnt(0)
; DEV void g1_phase(const Args& a, unsigned char* lds, int G) {
;     ...
;             for (int r = 0; r < 4; ++r) { float off = 0.f;
; #pragma unroll
;                 for (int pt = 0; pt < 4; ++pt) { const float tt = __shfl(cs[pt][r], (lane & 48) | 15); cs[pt][r] += off; off += tt; }
;                 tot[r] = off; }
;             if (gdir) {
; #pragma unroll
;                 for (int pt = 0; pt < 4; ++pt)
; #pragma unroll
;                     for (int r = 0; r < 4; ++r) cs[pt][r] = tot[r] - cs[pt][r] + gl[pt][r];
;             }
	v_pk_add_f32 v[64:65], v[64:65], 0 op_sel_hi:[1,0]
	v_pk_mul_f32 v[116:117], v[74:75], s[80:81] op_sel_hi:[1,0]
	v_pk_add_f32 v[142:143], v[64:65], v[142:143]
	s_nop 0
	v_mov_b32_dpp v114, v116 row_shr:1 row_mask:0xf bank_mask:0xf bound_ctrl:1
	v_mov_b32_dpp v115, v117 row_shr:1 row_mask:0xf bank_mask:0xf bound_ctrl:1
	v_pk_fma_f32 v[74:75], v[74:75], s[80:81], v[114:115] op_sel_hi:[1,0,1]
	v_pk_add_f32 v[144:145], v[142:143], v[144:145]
	s_nop 0
	v_mov_b32_dpp v114, v74 row_shr:2 row_mask:0xf bank_mask:0xf bound_ctrl:1
	v_mov_b32_dpp v115, v75 row_shr:2 row_mask:0xf bank_mask:0xf bound_ctrl:1
	v_pk_add_f32 v[74:75], v[74:75], v[114:115]
	s_nop 1
	v_mov_b32_dpp v114, v74 row_shr:4 row_mask:0xf bank_mask:0xf bound_ctrl:1
	v_mov_b32_dpp v115, v75 row_shr:4 row_mask:0xf bank_mask:0xf bound_ctrl:1
	v_pk_add_f32 v[74:75], v[74:75], v[114:115]
	s_nop 1
	v_mov_b32_dpp v114, v74 row_shr:8 row_mask:0xf bank_mask:0xf bound_ctrl:1
	v_mov_b32_dpp v115, v75 row_shr:8 row_mask:0xf bank_mask:0xf bound_ctrl:1
	v_pk_add_f32 v[114:115], v[74:75], v[114:115]
	v_pk_add_f32 v[74:75], v[70:71], v[64:65]
	v_pk_add_f32 v[70:71], v[66:67], v[142:143]
	ds_bpermute_b32 v142, v81, v76
	ds_bpermute_b32 v143, v81, v77
	v_pk_add_f32 v[64:65], v[76:77], 0 op_sel_hi:[1,0]
	v_mov_b32_dpp v76, v110 row_shr:1 row_mask:0xf bank_mask:0xf bound_ctrl:1
	v_mov_b32_dpp v77, v111 row_shr:1 row_mask:0xf bank_mask:0xf bound_ctrl:1
	v_pk_fma_f32 v[68:69], v[68:69], s[80:81], v[76:77] op_sel_hi:[1,0,1]
	ds_bpermute_b32 v148, v81, v114
	ds_bpermute_b32 v149, v81, v115
	v_mov_b32_dpp v76, v68 row_shr:2 row_mask:0xf bank_mask:0xf bound_ctrl:1
	v_mov_b32_dpp v77, v69 row_shr:2 row_mask:0xf bank_mask:0xf bound_ctrl:1
	v_pk_add_f32 v[68:69], v[68:69], v[76:77]
	v_pk_add_f32 v[66:67], v[114:115], v[144:145]
	s_waitcnt lgkmcnt(0)
	v_pk_add_f32 v[114:115], v[144:145], v[148:149]
	v_mov_b32_dpp v76, v68 row_shr:4 row_mask:0xf bank_mask:0xf bound_ctrl:1
	v_mov_b32_dpp v77, v69 row_shr:4 row_mask:0xf bank_mask:0xf bound_ctrl:1
	v_pk_add_f32 v[68:69], v[68:69], v[76:77]
	ds_bpermute_b32 v144, v81, v72
	ds_bpermute_b32 v145, v81, v73
	v_mov_b32_dpp v76, v68 row_shr:8 row_mask:0xf bank_mask:0xf bound_ctrl:1
	v_mov_b32_dpp v77, v69 row_shr:8 row_mask:0xf bank_mask:0xf bound_ctrl:1
	v_pk_add_f32 v[68:69], v[68:69], v[76:77]
	v_pk_add_f32 v[76:77], v[142:143], 0 op_sel_hi:[1,0]
	ds_bpermute_b32 v142, v81, v68
	ds_bpermute_b32 v143, v81, v69
	ds_bpermute_b32 v148, v81, v118
	ds_bpermute_b32 v149, v81, v119
	s_waitcnt lgkmcnt(4)
	v_pk_add_f32 v[144:145], v[76:77], v[144:145]
	v_pk_add_f32 v[76:77], v[72:73], v[76:77]
	s_waitcnt lgkmcnt(2)
	v_pk_add_f32 v[142:143], v[144:145], v[142:143]
	v_pk_add_f32 v[72:73], v[68:69], v[144:145]
	v_pk_add_f32 v[68:69], v[118:119], v[142:143]
	s_waitcnt lgkmcnt(0)
	v_pk_add_f32 v[118:119], v[142:143], v[148:149]
	s_and_saveexec_b64 s[0:1], s[4:5]
	s_cbranch_execz .LBB0_1534
	v_pk_add_f32 v[62:63], v[114:115], v[62:63] neg_lo:[0,1] neg_hi:[0,1]
	s_nop 0
	v_pk_add_f32 v[62:63], v[4:5], v[62:63]
	v_pk_add_f32 v[4:5], v[118:119], v[64:65] neg_lo:[0,1] neg_hi:[0,1]
	s_nop 0
	v_pk_add_f32 v[64:65], v[102:103], v[4:5]
	v_pk_add_f32 v[4:5], v[114:115], v[74:75] neg_lo:[0,1] neg_hi:[0,1]
	s_nop 0
	v_pk_add_f32 v[74:75], v[104:105], v[4:5]
	v_pk_add_f32 v[4:5], v[118:119], v[76:77] neg_lo:[0,1] neg_hi:[0,1]
	s_nop 0
	v_pk_add_f32 v[76:77], v[106:107], v[4:5]
	v_pk_add_f32 v[4:5], v[114:115], v[70:71] neg_lo:[0,1] neg_hi:[0,1]
	s_nop 0
	v_pk_add_f32 v[70:71], v[108:109], v[4:5]
	v_pk_add_f32 v[4:5], v[118:119], v[72:73] neg_lo:[0,1] neg_hi:[0,1]
	s_nop 0
	v_pk_add_f32 v[72:73], v[110:111], v[4:5]
	v_pk_add_f32 v[4:5], v[114:115], v[66:67] neg_lo:[0,1] neg_hi:[0,1]
	s_nop 0
	v_pk_add_f32 v[66:67], v[116:117], v[4:5]
	v_pk_add_f32 v[4:5], v[118:119], v[68:69] neg_lo:[0,1] neg_hi:[0,1]
	s_nop 0
	v_pk_add_f32 v[68:69], v[112:113], v[4:5]
